# grid barrier: agent acquire (buffer_inv sc1) issued at arrival behind the arrival atomic instead of after the release
# speedup vs baseline: 1.0568x; 1.0188x over previous
.LBB0_86:
	s_or_b64 exec, exec, s[8:9]
	buffer_inv sc1
	v_cvt_f32_u32_e32 v4, v2
	s_waitcnt vmcnt(1)
	v_readfirstlane_b32 s6, v3
	v_rcp_iflag_f32_e32 v4, v4
	s_nop 0
	v_add_u32_e32 v1, s6, v1
	v_add_u32_e32 v5, 1, v1
	v_mul_f32_e32 v3, 0x4f7ffffe, v4
	v_cvt_u32_f32_e32 v3, v3
	v_sub_u32_e32 v4, 0, v2
	v_mul_lo_u32 v4, v4, v3
	v_mul_hi_u32 v4, v3, v4
	v_add_u32_e32 v3, v3, v4
	v_mul_hi_u32 v3, v1, v3
	v_mul_lo_u32 v4, v3, v2
	v_sub_u32_e32 v1, v1, v4
	v_add_u32_e32 v6, 1, v3
	v_cmp_ge_u32_e32 vcc, v1, v2
	v_sub_u32_e32 v4, v1, v2
	s_nop 0
	v_cndmask_b32_e32 v3, v3, v6, vcc
	v_cndmask_b32_e32 v1, v1, v4, vcc
	v_add_u32_e32 v4, 1, v3
	v_cmp_ge_u32_e32 vcc, v1, v2
	s_nop 1
	v_cndmask_b32_e32 v1, v3, v4, vcc
	v_mad_u64_u32 v[2:3], s[6:7], v2, v1, v[2:3]
	v_cmp_ne_u32_e32 vcc, v5, v2
	s_and_saveexec_b64 s[6:7], vcc
	s_xor_b64 s[6:7], exec, s[6:7]
	s_cbranch_execz .LBB0_100
	v_mov_b32_e32 v0, 0x2000
	global_load_dword v0, v0, s[4:5] offset:1024 sc1
	s_add_u32 s12, s4, 0x2400
	s_addc_u32 s13, s5, 0
	s_waitcnt vmcnt(0)
	v_cmp_eq_u32_e32 vcc, v0, v1
	s_and_saveexec_b64 s[8:9], vcc
	s_cbranch_execz .LBB0_99
	s_add_u32 s10, s94, 0x1d11e200
	s_addc_u32 s11, s95, 0
	s_mov_b32 s24, 1
	s_mov_b64 s[14:15], 0
	v_mov_b32_e32 v0, 0
	s_branch .LBB0_90

.LBB0_99:
	s_or_b64 exec, exec, s[8:9]
	s_waitcnt vmcnt(0) lgkmcnt(0)
	s_waitcnt vmcnt(0)

.LBB0_117:
	s_or_b64 exec, exec, s[6:7]
	s_mov_b64 s[6:7], exec
	v_mbcnt_lo_u32_b32 v0, s6, 0
	v_mbcnt_hi_u32_b32 v0, s7, v0
	v_cmp_eq_u32_e32 vcc, 0, v0
	s_waitcnt vmcnt(0)
	s_and_saveexec_b64 s[8:9], vcc
	s_cbranch_execz .LBB0_119
	s_bcnt1_i32_b64 s6, s[6:7]
	v_mov_b32_e32 v0, 0x2000
	v_mov_b32_e32 v1, s6
	global_atomic_add v0, v1, s[4:5] offset:1024

.LBB0_376:
	s_or_b64 exec, exec, s[6:7]
	buffer_inv sc1
	v_cvt_f32_u32_e32 v4, v2
	s_waitcnt vmcnt(1)
	v_readfirstlane_b32 s4, v3
	v_rcp_iflag_f32_e32 v4, v4
	s_nop 0
	v_add_u32_e32 v1, s4, v1
	v_add_u32_e32 v5, 1, v1
	v_mul_f32_e32 v3, 0x4f7ffffe, v4
	v_cvt_u32_f32_e32 v3, v3
	v_sub_u32_e32 v4, 0, v2
	v_mul_lo_u32 v4, v4, v3
	v_mul_hi_u32 v4, v3, v4
	v_add_u32_e32 v3, v3, v4
	v_mul_hi_u32 v3, v1, v3
	v_mul_lo_u32 v4, v3, v2
	v_sub_u32_e32 v1, v1, v4
	v_add_u32_e32 v6, 1, v3
	v_cmp_ge_u32_e32 vcc, v1, v2
	v_sub_u32_e32 v4, v1, v2
	s_nop 0
	v_cndmask_b32_e32 v3, v3, v6, vcc
	v_cndmask_b32_e32 v1, v1, v4, vcc
	v_add_u32_e32 v4, 1, v3
	v_cmp_ge_u32_e32 vcc, v1, v2
	s_nop 1
	v_cndmask_b32_e32 v1, v3, v4, vcc
	v_mad_u64_u32 v[2:3], s[4:5], v2, v1, v[2:3]
	v_cmp_ne_u32_e32 vcc, v5, v2
	s_and_saveexec_b64 s[4:5], vcc
	s_xor_b64 s[4:5], exec, s[4:5]
	s_cbranch_execz .LBB0_390
	v_mov_b32_e32 v0, 0x2000
	global_load_dword v0, v0, s[2:3] offset:1024 sc1
	s_add_u32 s10, s2, 0x2400
	s_addc_u32 s11, s3, 0
	s_waitcnt vmcnt(0)
	v_cmp_eq_u32_e32 vcc, v0, v1
	s_and_saveexec_b64 s[6:7], vcc
	s_cbranch_execz .LBB0_389
	s_add_u32 s8, s94, 0x1d11e200
	s_addc_u32 s9, s95, 0
	s_mov_b32 s22, 1
	s_mov_b64 s[12:13], 0
	v_mov_b32_e32 v0, 0
	s_branch .LBB0_380

.LBB0_389:
	s_or_b64 exec, exec, s[6:7]
	s_waitcnt vmcnt(0) lgkmcnt(0)
	s_waitcnt vmcnt(0)

.LBB0_407:
	s_or_b64 exec, exec, s[4:5]
	s_mov_b64 s[4:5], exec
	v_mbcnt_lo_u32_b32 v0, s4, 0
	v_mbcnt_hi_u32_b32 v0, s5, v0
	v_cmp_eq_u32_e32 vcc, 0, v0
	s_waitcnt vmcnt(0)
	s_and_saveexec_b64 s[6:7], vcc
	s_cbranch_execz .LBB0_409
	s_bcnt1_i32_b64 s4, s[4:5]
	v_mov_b32_e32 v0, 0x2000
	v_mov_b32_e32 v1, s4
	global_atomic_add v0, v1, s[2:3] offset:1024

.LBB0_981:
	s_or_b64 exec, exec, s[10:11]
	buffer_inv sc1
	v_cvt_f32_u32_e32 v4, v2
	s_waitcnt vmcnt(1)
	v_readfirstlane_b32 s8, v3
	v_rcp_iflag_f32_e32 v4, v4
	s_nop 0
	v_add_u32_e32 v1, s8, v1
	v_add_u32_e32 v5, 1, v1
	v_mul_f32_e32 v3, 0x4f7ffffe, v4
	v_cvt_u32_f32_e32 v3, v3
	v_sub_u32_e32 v4, 0, v2
	v_mul_lo_u32 v4, v4, v3
	v_mul_hi_u32 v4, v3, v4
	v_add_u32_e32 v3, v3, v4
	v_mul_hi_u32 v3, v1, v3
	v_mul_lo_u32 v4, v3, v2
	v_sub_u32_e32 v1, v1, v4
	v_add_u32_e32 v6, 1, v3
	v_cmp_ge_u32_e32 vcc, v1, v2
	v_sub_u32_e32 v4, v1, v2
	s_nop 0
	v_cndmask_b32_e32 v3, v3, v6, vcc
	v_cndmask_b32_e32 v1, v1, v4, vcc
	v_add_u32_e32 v4, 1, v3
	v_cmp_ge_u32_e32 vcc, v1, v2
	s_nop 1
	v_cndmask_b32_e32 v1, v3, v4, vcc
	v_mad_u64_u32 v[2:3], s[8:9], v2, v1, v[2:3]
	v_cmp_ne_u32_e32 vcc, v5, v2
	s_and_saveexec_b64 s[8:9], vcc
	s_xor_b64 s[8:9], exec, s[8:9]
	s_cbranch_execz .LBB0_995
	v_mov_b32_e32 v0, 0x2000
	global_load_dword v0, v0, s[6:7] offset:1024 sc1
	s_add_u32 s14, s6, 0x2400
	s_addc_u32 s15, s7, 0
	s_waitcnt vmcnt(0)
	v_cmp_eq_u32_e32 vcc, v0, v1
	s_and_saveexec_b64 s[10:11], vcc
	s_cbranch_execz .LBB0_994
	s_add_u32 s12, s94, 0x1d11e200
	s_addc_u32 s13, s95, 0
	s_mov_b32 s26, 1
	s_mov_b64 s[16:17], 0
	v_mov_b32_e32 v0, 0
	s_branch .LBB0_985

.LBB0_994:
	s_or_b64 exec, exec, s[10:11]
	s_waitcnt vmcnt(0) lgkmcnt(0)
	s_waitcnt vmcnt(0)

.LBB0_1012:
	s_or_b64 exec, exec, s[8:9]
	s_mov_b64 s[8:9], exec
	v_mbcnt_lo_u32_b32 v0, s8, 0
	v_mbcnt_hi_u32_b32 v0, s9, v0
	v_cmp_eq_u32_e32 vcc, 0, v0
	s_waitcnt vmcnt(0)
	s_and_saveexec_b64 s[10:11], vcc
	s_cbranch_execz .LBB0_1014
	s_bcnt1_i32_b64 s8, s[8:9]
	v_mov_b32_e32 v0, 0x2000
	v_mov_b32_e32 v1, s8
	global_atomic_add v0, v1, s[6:7] offset:1024

.LBB0_1848:
	s_or_b64 exec, exec, s[4:5]
	buffer_inv sc1
	v_cvt_f32_u32_e32 v4, v2
	s_waitcnt vmcnt(1)
	v_readfirstlane_b32 s2, v3
	v_rcp_iflag_f32_e32 v4, v4
	s_nop 0
	v_add_u32_e32 v1, s2, v1
	v_add_u32_e32 v5, 1, v1
	v_mul_f32_e32 v3, 0x4f7ffffe, v4
	v_cvt_u32_f32_e32 v3, v3
	v_sub_u32_e32 v4, 0, v2
	v_mul_lo_u32 v4, v4, v3
	v_mul_hi_u32 v4, v3, v4
	v_add_u32_e32 v3, v3, v4
	v_mul_hi_u32 v3, v1, v3
	v_mul_lo_u32 v4, v3, v2
	v_sub_u32_e32 v1, v1, v4
	v_add_u32_e32 v6, 1, v3
	v_cmp_ge_u32_e32 vcc, v1, v2
	v_sub_u32_e32 v4, v1, v2
	s_nop 0
	v_cndmask_b32_e32 v3, v3, v6, vcc
	v_cndmask_b32_e32 v1, v1, v4, vcc
	v_add_u32_e32 v4, 1, v3
	v_cmp_ge_u32_e32 vcc, v1, v2
	s_nop 1
	v_cndmask_b32_e32 v1, v3, v4, vcc
	v_mad_u64_u32 v[2:3], s[2:3], v2, v1, v[2:3]
	v_cmp_ne_u32_e32 vcc, v5, v2
	s_and_saveexec_b64 s[2:3], vcc
	s_xor_b64 s[2:3], exec, s[2:3]
	s_cbranch_execz .LBB0_1862
	v_mov_b32_e32 v0, 0x2000
	global_load_dword v0, v0, s[0:1] offset:1024 sc1
	s_add_u32 s8, s0, 0x2400
	s_addc_u32 s9, s1, 0
	s_waitcnt vmcnt(0)
	v_cmp_eq_u32_e32 vcc, v0, v1
	s_and_saveexec_b64 s[4:5], vcc
	s_cbranch_execz .LBB0_1861
	s_add_u32 s6, s94, 0x1d11e200
	s_addc_u32 s7, s95, 0
	s_mov_b32 s20, 1
	s_mov_b64 s[10:11], 0
	v_mov_b32_e32 v0, 0
	s_branch .LBB0_1852

.LBB0_1861:
	s_or_b64 exec, exec, s[4:5]
	s_waitcnt vmcnt(0) lgkmcnt(0)
	s_waitcnt vmcnt(0)

.LBB0_1879:
	s_or_b64 exec, exec, s[2:3]
	s_mov_b64 s[2:3], exec
	v_mbcnt_lo_u32_b32 v0, s2, 0
	v_mbcnt_hi_u32_b32 v0, s3, v0
	v_cmp_eq_u32_e32 vcc, 0, v0
	s_waitcnt vmcnt(0)
	s_and_saveexec_b64 s[4:5], vcc
	s_cbranch_execz .LBB0_1881
	s_bcnt1_i32_b64 s2, s[2:3]
	v_mov_b32_e32 v0, 0x2000
	v_mov_b32_e32 v1, s2
	global_atomic_add v0, v1, s[0:1] offset:1024
